# differential-attention steps: issue the K/Q fragment LDS reads immediately after each QK MFMA (ahead of the exp work)
# baseline (speedup 1.0000x reference)
.LBB0_563:
	s_add_i32 s13, s12, -1
	s_min_u32 s34, s13, s4
	s_lshl_b64 s[30:31], s[34:35], 13
	v_lshl_add_u64 v[2:3], v[224:225], 0, s[30:31]
	global_load_dwordx4 v[196:199], v[2:3], off
	v_add_co_u32_e32 v2, vcc, s1, v218
	s_nop 1
	v_addc_co_u32_e32 v3, vcc, -1, v219, vcc
	global_load_dwordx4 v[200:203], v[2:3], off offset:-4096
	global_load_dwordx4 v[204:207], v[2:3], off
	ds_read_b128 v[2:5], v243 offset:4608
	ds_read_b128 v[6:9], v243
	ds_read_b128 v[12:15], v242 offset:59392
	s_waitcnt lgkmcnt(0)
	v_mfma_f32_32x32x16_bf16 v[160:175], v[6:9], v[12:15], v[96:111]
	ds_read_b128 v[112:115], v243 offset:32
	ds_read_b128 v[116:119], v242 offset:60416
	v_exp_f32_e32 v0, v128
	v_exp_f32_e32 v6, v129
	v_add_f32_e32 v7, 0, v0
	v_add_f32_e32 v11, v6, v7
	v_cvt_pk_bf16_f32 v10, v0, v6
	v_mfma_f32_32x32x16_bf16 v[144:159], v[2:5], v[12:15], v[96:111]
	ds_read_b128 v[6:9], v243 offset:4640
	v_exp_f32_e32 v0, v130
	v_exp_f32_e32 v120, v131
	v_add_f32_e32 v121, v0, v11
	v_cvt_pk_bf16_f32 v11, v0, v120
	v_add_f32_e32 v0, v120, v121
	s_waitcnt lgkmcnt(1)
	v_mfma_f32_32x32x16_bf16 v[160:175], v[112:115], v[116:119], v[160:175]
	ds_read_b128 v[2:5], v243 offset:64
	ds_read_b128 v[120:123], v242 offset:61440
	v_exp_f32_e32 v12, v132
	v_exp_f32_e32 v13, v133
	v_add_f32_e32 v0, v12, v0
	v_add_f32_e32 v0, v13, v0
	v_cvt_pk_bf16_f32 v12, v12, v13
	s_waitcnt lgkmcnt(2)
	v_mfma_f32_32x32x16_bf16 v[144:159], v[6:9], v[116:119], v[144:159]
	ds_read_b128 v[112:115], v243 offset:4672
	v_exp_f32_e32 v6, v134
	v_exp_f32_e32 v7, v135
	v_add_f32_e32 v0, v6, v0
	v_add_f32_e32 v0, v7, v0
	v_cvt_pk_bf16_f32 v13, v6, v7
	s_waitcnt lgkmcnt(1)
	v_mfma_f32_32x32x16_bf16 v[160:175], v[2:5], v[120:123], v[160:175]
	ds_read_b128 v[116:119], v243 offset:96
	ds_read_b128 v[124:127], v242 offset:62464
	v_exp_f32_e32 v2, v136
	v_exp_f32_e32 v3, v137
	v_add_f32_e32 v0, v2, v0
	v_add_f32_e32 v0, v3, v0
	v_cvt_pk_bf16_f32 v6, v2, v3
	s_waitcnt lgkmcnt(2)
	v_mfma_f32_32x32x16_bf16 v[144:159], v[112:115], v[120:123], v[144:159]
	ds_read_b128 v[2:5], v243 offset:4704
	v_exp_f32_e32 v7, v138
	v_exp_f32_e32 v8, v139
	v_add_f32_e32 v0, v7, v0
	v_add_f32_e32 v0, v8, v0
	v_cvt_pk_bf16_f32 v7, v7, v8
	s_waitcnt lgkmcnt(1)
	v_mfma_f32_32x32x16_bf16 v[160:175], v[116:119], v[124:127], v[160:175]
	ds_read_b64_tr_b16 v[112:113], v244 offset:18432
	ds_read_b64_tr_b16 v[114:115], v244 offset:20992
	v_exp_f32_e32 v8, v140
	v_exp_f32_e32 v9, v141
	v_add_f32_e32 v0, v8, v0
	v_add_f32_e32 v0, v9, v0
	v_cvt_pk_bf16_f32 v8, v8, v9
	s_waitcnt lgkmcnt(2)
	v_mfma_f32_32x32x16_bf16 v[144:159], v[2:5], v[124:127], v[144:159]
	ds_read_b64_tr_b16 v[116:117], v244 offset:18496
	ds_read_b64_tr_b16 v[118:119], v244 offset:21056
	v_exp_f32_e32 v9, v142
	v_exp_f32_e32 v14, v143
	v_add_f32_e32 v0, v9, v0
	v_add_f32_e32 v0, v14, v0
	v_cvt_pk_bf16_f32 v9, v9, v14
	s_waitcnt lgkmcnt(2)
	v_mfma_f32_32x32x16_bf16 v[64:79], v[112:115], v[188:191], v[64:79]
	ds_read_b64_tr_b16 v[120:121], v244 offset:18560
	ds_read_b64_tr_b16 v[122:123], v244 offset:21120
	v_exp_f32_e32 v2, v80
	v_max3_f32 v3, v160, s33, v144
	v_add_f32_e32 v0, v2, v0
	s_waitcnt lgkmcnt(2)
	v_mfma_f32_32x32x16_bf16 v[48:63], v[116:119], v[188:191], v[48:63]
	ds_read_b64_tr_b16 v[112:113], v244 offset:18624
	ds_read_b64_tr_b16 v[114:115], v244 offset:21184
	v_exp_f32_e32 v4, v81
	v_max3_f32 v3, v3, v161, v145
	v_add_f32_e32 v0, v4, v0
	v_cvt_pk_bf16_f32 v2, v2, v4
	s_waitcnt lgkmcnt(2)
	v_mfma_f32_32x32x16_bf16 v[32:47], v[120:123], v[188:191], v[32:47]
	ds_read_b64_tr_b16 v[116:117], v244 offset:23552
	ds_read_b64_tr_b16 v[118:119], v244 offset:26112
	v_exp_f32_e32 v4, v82
	v_max3_f32 v5, v3, v162, v146
	v_add_f32_e32 v0, v4, v0
	s_waitcnt lgkmcnt(2)
	v_mfma_f32_32x32x16_bf16 v[16:31], v[112:115], v[188:191], v[16:31]
	ds_read_b64_tr_b16 v[120:121], v244 offset:23616
	ds_read_b64_tr_b16 v[122:123], v244 offset:26176
	v_exp_f32_e32 v3, v83
	s_nop 0
	v_add_f32_e32 v0, v3, v0
	v_cvt_pk_bf16_f32 v3, v4, v3
	v_max3_f32 v4, v5, v163, v147
	s_waitcnt lgkmcnt(2)
	v_mfma_f32_32x32x16_bf16 v[64:79], v[116:119], v[184:187], v[64:79]
	ds_read_b64_tr_b16 v[80:81], v244 offset:23680
	ds_read_b64_tr_b16 v[82:83], v244 offset:26240
	v_exp_f32_e32 v5, v84
	v_max3_f32 v14, v4, v164, v148
	v_add_f32_e32 v0, v5, v0
	s_waitcnt lgkmcnt(2)
	v_mfma_f32_32x32x16_bf16 v[48:63], v[120:123], v[184:187], v[48:63]
	ds_read_b64_tr_b16 v[112:113], v244 offset:23744
	ds_read_b64_tr_b16 v[114:115], v244 offset:26304
	v_exp_f32_e32 v4, v85
	s_nop 0
	v_add_f32_e32 v0, v4, v0
	v_cvt_pk_bf16_f32 v4, v5, v4
	v_max3_f32 v5, v14, v165, v149
	s_waitcnt lgkmcnt(2)
	v_mfma_f32_32x32x16_bf16 v[32:47], v[80:83], v[184:187], v[32:47]
	ds_read_b64_tr_b16 v[116:117], v244 offset:28672
	ds_read_b64_tr_b16 v[118:119], v244 offset:31232
	v_exp_f32_e32 v14, v86
	v_max3_f32 v15, v5, v166, v150
	v_add_f32_e32 v0, v14, v0
	s_waitcnt lgkmcnt(2)
	v_mfma_f32_32x32x16_bf16 v[16:31], v[112:115], v[184:187], v[16:31]
	ds_read_b64_tr_b16 v[80:81], v244 offset:28736
	ds_read_b64_tr_b16 v[82:83], v244 offset:31296
	v_exp_f32_e32 v5, v87
	s_nop 0
	v_add_f32_e32 v0, v5, v0
	v_cvt_pk_bf16_f32 v5, v14, v5
	v_max3_f32 v14, v15, v167, v151
	s_waitcnt lgkmcnt(2)
	v_mfma_f32_32x32x16_bf16 v[64:79], v[116:119], v[176:179], v[64:79]
	ds_read_b64_tr_b16 v[84:85], v244 offset:28800
	ds_read_b64_tr_b16 v[86:87], v244 offset:31360
	v_exp_f32_e32 v15, v88
	v_max3_f32 v14, v14, v168, v152
	v_add_f32_e32 v0, v15, v0
	s_waitcnt lgkmcnt(2)
	v_mfma_f32_32x32x16_bf16 v[48:63], v[80:83], v[176:179], v[48:63]
	ds_read_b64_tr_b16 v[112:113], v244 offset:28864
	ds_read_b64_tr_b16 v[114:115], v244 offset:31424
	v_exp_f32_e32 v80, v89
	v_max3_f32 v14, v14, v169, v153
	v_add_f32_e32 v0, v80, v0
	v_cvt_pk_bf16_f32 v192, v15, v80
	s_waitcnt lgkmcnt(2)
	v_mfma_f32_32x32x16_bf16 v[32:47], v[84:87], v[176:179], v[32:47]
	ds_read_b64_tr_b16 v[80:81], v244 offset:33792
	ds_read_b64_tr_b16 v[82:83], v244 offset:36352
	v_exp_f32_e32 v15, v90
	v_max3_f32 v14, v14, v170, v154
	v_add_f32_e32 v0, v15, v0
	s_waitcnt lgkmcnt(2)
	v_mfma_f32_32x32x16_bf16 v[16:31], v[112:115], v[176:179], v[16:31]
	ds_read_b64_tr_b16 v[84:85], v244 offset:33856
	ds_read_b64_tr_b16 v[86:87], v244 offset:36416
	v_exp_f32_e32 v88, v91
	v_max3_f32 v14, v14, v171, v155
	v_add_f32_e32 v0, v88, v0
	v_cvt_pk_bf16_f32 v193, v15, v88
	s_waitcnt lgkmcnt(2)
	v_mfma_f32_32x32x16_bf16 v[64:79], v[80:83], v[180:183], v[64:79]
	ds_read_b64_tr_b16 v[88:89], v244 offset:33920
	ds_read_b64_tr_b16 v[90:91], v244 offset:36480
	v_exp_f32_e32 v15, v92
	v_max3_f32 v14, v14, v172, v156
	v_add_f32_e32 v0, v15, v0
	s_waitcnt lgkmcnt(2)
	v_mfma_f32_32x32x16_bf16 v[48:63], v[84:87], v[180:183], v[48:63]
	ds_read_b64_tr_b16 v[80:81], v244 offset:33984
	ds_read_b64_tr_b16 v[82:83], v244 offset:36544
	v_exp_f32_e32 v84, v93
	v_max3_f32 v14, v14, v173, v157
	v_add_f32_e32 v0, v84, v0
	v_cvt_pk_bf16_f32 v194, v15, v84
	s_waitcnt lgkmcnt(2)
	v_mfma_f32_32x32x16_bf16 v[32:47], v[88:91], v[180:183], v[32:47]
	v_exp_f32_e32 v15, v94
	v_max3_f32 v14, v14, v174, v158
	v_add_f32_e32 v0, v15, v0
	s_waitcnt lgkmcnt(0)
	v_mfma_f32_32x32x16_bf16 v[16:31], v[80:83], v[180:183], v[16:31]
	v_exp_f32_e32 v80, v95
	s_nop 0
	v_add_f32_e32 v0, v80, v0
	v_cvt_pk_bf16_f32 v195, v15, v80
	v_max3_f32 v15, v14, v175, v159
	v_mov_b32_e32 v14, v0
	s_nop 1
	v_permlane32_swap_b32_e32 v0, v14
	v_cmp_gt_f32_e32 vcc, 1.0, v226
	s_cbranch_vccz .LBB0_565
	v_pk_mul_f32 v[78:79], v[226:227], v[78:79] op_sel_hi:[0,1]
	v_pk_mul_f32 v[76:77], v[226:227], v[76:77] op_sel_hi:[0,1]
	v_pk_mul_f32 v[74:75], v[226:227], v[74:75] op_sel_hi:[0,1]
	v_pk_mul_f32 v[72:73], v[226:227], v[72:73] op_sel_hi:[0,1]
	v_pk_mul_f32 v[70:71], v[226:227], v[70:71] op_sel_hi:[0,1]
	v_pk_mul_f32 v[68:69], v[226:227], v[68:69] op_sel_hi:[0,1]
	v_pk_mul_f32 v[66:67], v[226:227], v[66:67] op_sel_hi:[0,1]
	v_pk_mul_f32 v[64:65], v[226:227], v[64:65] op_sel_hi:[0,1]
	v_pk_mul_f32 v[62:63], v[226:227], v[62:63] op_sel_hi:[0,1]
	v_pk_mul_f32 v[60:61], v[226:227], v[60:61] op_sel_hi:[0,1]
	v_pk_mul_f32 v[58:59], v[226:227], v[58:59] op_sel_hi:[0,1]
	v_pk_mul_f32 v[56:57], v[226:227], v[56:57] op_sel_hi:[0,1]
	v_pk_mul_f32 v[54:55], v[226:227], v[54:55] op_sel_hi:[0,1]
	v_pk_mul_f32 v[52:53], v[226:227], v[52:53] op_sel_hi:[0,1]
	v_pk_mul_f32 v[50:51], v[226:227], v[50:51] op_sel_hi:[0,1]
	v_pk_mul_f32 v[48:49], v[226:227], v[48:49] op_sel_hi:[0,1]
	v_pk_mul_f32 v[46:47], v[226:227], v[46:47] op_sel_hi:[0,1]
	v_pk_mul_f32 v[44:45], v[226:227], v[44:45] op_sel_hi:[0,1]
	v_pk_mul_f32 v[42:43], v[226:227], v[42:43] op_sel_hi:[0,1]
	v_pk_mul_f32 v[40:41], v[226:227], v[40:41] op_sel_hi:[0,1]
	v_pk_mul_f32 v[38:39], v[226:227], v[38:39] op_sel_hi:[0,1]
	v_pk_mul_f32 v[36:37], v[226:227], v[36:37] op_sel_hi:[0,1]
	v_pk_mul_f32 v[34:35], v[226:227], v[34:35] op_sel_hi:[0,1]
	v_pk_mul_f32 v[32:33], v[226:227], v[32:33] op_sel_hi:[0,1]
	v_pk_mul_f32 v[30:31], v[226:227], v[30:31] op_sel_hi:[0,1]
	v_pk_mul_f32 v[28:29], v[226:227], v[28:29] op_sel_hi:[0,1]
	v_pk_mul_f32 v[26:27], v[226:227], v[26:27] op_sel_hi:[0,1]
	v_pk_mul_f32 v[24:25], v[226:227], v[24:25] op_sel_hi:[0,1]
	v_pk_mul_f32 v[22:23], v[226:227], v[22:23] op_sel_hi:[0,1]
	v_pk_mul_f32 v[20:21], v[226:227], v[20:21] op_sel_hi:[0,1]
	v_pk_mul_f32 v[18:19], v[226:227], v[18:19] op_sel_hi:[0,1]
	v_pk_mul_f32 v[16:17], v[226:227], v[16:17] op_sel_hi:[0,1]

.LBB0_568:
	s_min_u32 s34, s12, s4
	s_waitcnt vmcnt(2)
	ds_write_b128 v241, v[196:199] offset:9216
	s_waitcnt vmcnt(1)
	ds_write_b128 v240, v[200:203] offset:38912
	s_waitcnt vmcnt(0)
	ds_write_b128 v240, v[204:207] offset:49152
	s_lshl_b64 s[30:31], s[34:35], 13
	s_waitcnt lgkmcnt(0)
	s_barrier
	v_lshl_add_u64 v[80:81], v[224:225], 0, s[30:31]
	global_load_dwordx4 v[196:199], v[80:81], off
	global_load_dwordx4 v[200:203], v[218:219], off offset:-4096
	global_load_dwordx4 v[204:207], v[218:219], off
	ds_read_b128 v[176:179], v243 offset:13824
	ds_read_b128 v[80:83], v243 offset:9216
	ds_read_b128 v[180:183], v242 offset:59392
	s_waitcnt lgkmcnt(0)
	v_mfma_f32_32x32x16_bf16 v[128:143], v[80:83], v[180:183], v[112:127]
	ds_read_b128 v[184:187], v243 offset:9248
	ds_read_b128 v[248:251], v242 offset:60416
	v_exp_f32_e32 v15, v160
	v_exp_f32_e32 v80, v161
	v_add_f32_e32 v81, 0, v15
	v_add_f32_e32 v81, v80, v81
	v_cvt_pk_bf16_f32 v188, v15, v80
	v_exp_f32_e32 v15, v162
	v_exp_f32_e32 v80, v163
	ds_read_b128 v[160:163], v243 offset:13856
	v_add_f32_e32 v81, v15, v81
	v_cvt_pk_bf16_f32 v189, v15, v80
	v_add_f32_e32 v15, v80, v81
	v_mfma_f32_32x32x16_bf16 v[80:95], v[176:179], v[180:183], v[112:127]
	s_waitcnt lgkmcnt(1)
	v_mfma_f32_32x32x16_bf16 v[128:143], v[184:187], v[248:251], v[128:143]
	ds_read_b128 v[176:179], v243 offset:9280
	ds_read_b128 v[180:183], v242 offset:61440
	v_exp_f32_e32 v164, v164
	v_exp_f32_e32 v165, v165
	v_add_f32_e32 v15, v164, v15
	v_cvt_pk_bf16_f32 v190, v164, v165
	v_add_f32_e32 v15, v165, v15
	s_waitcnt lgkmcnt(2)
	v_mfma_f32_32x32x16_bf16 v[80:95], v[160:163], v[248:251], v[80:95]
	ds_read_b128 v[234:237], v243 offset:13888
	v_exp_f32_e32 v160, v166
	v_exp_f32_e32 v161, v167
	v_add_f32_e32 v15, v160, v15
	v_cvt_pk_bf16_f32 v191, v160, v161
	v_add_f32_e32 v15, v161, v15
	s_waitcnt lgkmcnt(1)
	v_mfma_f32_32x32x16_bf16 v[128:143], v[176:179], v[180:183], v[128:143]
	ds_read_b128 v[160:163], v243 offset:9312
	ds_read_b128 v[164:167], v242 offset:62464
	v_exp_f32_e32 v168, v168
	v_exp_f32_e32 v169, v169
	v_add_f32_e32 v15, v168, v15
	v_cvt_pk_bf16_f32 v184, v168, v169
	v_add_f32_e32 v15, v169, v15
	s_waitcnt lgkmcnt(2)
	v_mfma_f32_32x32x16_bf16 v[80:95], v[234:237], v[180:183], v[80:95]
	ds_read_b128 v[176:179], v243 offset:13920
	v_exp_f32_e32 v168, v170
	v_exp_f32_e32 v169, v171
	v_add_f32_e32 v15, v168, v15
	v_cvt_pk_bf16_f32 v185, v168, v169
	v_add_f32_e32 v15, v169, v15
	s_waitcnt lgkmcnt(1)
	v_mfma_f32_32x32x16_bf16 v[128:143], v[160:163], v[164:167], v[128:143]
	ds_read_b64_tr_b16 v[168:169], v244 offset:38912
	ds_read_b64_tr_b16 v[170:171], v244 offset:41472
	v_exp_f32_e32 v160, v172
	v_exp_f32_e32 v161, v173
	v_add_f32_e32 v15, v160, v15
	v_cvt_pk_bf16_f32 v186, v160, v161
	v_add_f32_e32 v15, v161, v15
	s_waitcnt lgkmcnt(2)
	v_mfma_f32_32x32x16_bf16 v[80:95], v[176:179], v[164:167], v[80:95]
	ds_read_b64_tr_b16 v[160:161], v244 offset:38976
	ds_read_b64_tr_b16 v[162:163], v244 offset:41536
	v_exp_f32_e32 v172, v174
	v_exp_f32_e32 v173, v175
	v_add_f32_e32 v15, v172, v15
	v_cvt_pk_bf16_f32 v187, v172, v173
	v_add_f32_e32 v15, v173, v15
	s_waitcnt lgkmcnt(2)
	v_mfma_f32_32x32x16_bf16 v[64:79], v[168:171], v[10:13], v[64:79]
	ds_read_b64_tr_b16 v[164:165], v244 offset:39040
	ds_read_b64_tr_b16 v[166:167], v244 offset:41600
	v_exp_f32_e32 v144, v144
	v_max3_f32 v172, v128, s33, v80
	v_add_f32_e32 v15, v144, v15
	s_waitcnt lgkmcnt(2)
	v_mfma_f32_32x32x16_bf16 v[48:63], v[160:163], v[10:13], v[48:63]
	ds_read_b64_tr_b16 v[168:169], v244 offset:39104
	ds_read_b64_tr_b16 v[170:171], v244 offset:41664
	v_exp_f32_e32 v145, v145
	s_nop 0
	v_cvt_pk_bf16_f32 v176, v144, v145
	v_max3_f32 v144, v172, v129, v81
	v_add_f32_e32 v15, v145, v15
	s_waitcnt lgkmcnt(2)
	v_mfma_f32_32x32x16_bf16 v[32:47], v[164:167], v[10:13], v[32:47]
	ds_read_b64_tr_b16 v[160:161], v244 offset:44032
	ds_read_b64_tr_b16 v[162:163], v244 offset:46592
	v_exp_f32_e32 v145, v146
	v_max3_f32 v144, v144, v130, v82
	v_add_f32_e32 v15, v145, v15
	s_waitcnt lgkmcnt(2)
	v_mfma_f32_32x32x16_bf16 v[16:31], v[168:171], v[10:13], v[16:31]
	ds_read_b64_tr_b16 v[164:165], v244 offset:44096
	ds_read_b64_tr_b16 v[166:167], v244 offset:46656
	v_exp_f32_e32 v10, v147
	v_max3_f32 v144, v144, v131, v83
	v_cvt_pk_bf16_f32 v177, v145, v10
	v_add_f32_e32 v15, v10, v15
	s_waitcnt lgkmcnt(2)
	v_mfma_f32_32x32x16_bf16 v[64:79], v[160:163], v[6:9], v[64:79]
	ds_read_b64_tr_b16 v[10:11], v244 offset:44160
	ds_read_b64_tr_b16 v[12:13], v244 offset:46720
	v_exp_f32_e32 v148, v148
	v_max3_f32 v160, v144, v132, v84
	v_add_f32_e32 v15, v148, v15
	s_waitcnt lgkmcnt(2)
	v_mfma_f32_32x32x16_bf16 v[48:63], v[164:167], v[6:9], v[48:63]
	ds_read_b64_tr_b16 v[144:145], v244 offset:44224
	ds_read_b64_tr_b16 v[146:147], v244 offset:46784
	v_exp_f32_e32 v149, v149
	s_nop 0
	v_cvt_pk_bf16_f32 v178, v148, v149
	v_max3_f32 v148, v160, v133, v85
	v_add_f32_e32 v15, v149, v15
	s_waitcnt lgkmcnt(2)
	v_mfma_f32_32x32x16_bf16 v[32:47], v[10:13], v[6:9], v[32:47]
	ds_read_b64_tr_b16 v[160:161], v244 offset:49152
	ds_read_b64_tr_b16 v[162:163], v244 offset:51712
	v_exp_f32_e32 v149, v150
	v_max3_f32 v148, v148, v134, v86
	v_add_f32_e32 v15, v149, v15
	s_waitcnt lgkmcnt(2)
	v_mfma_f32_32x32x16_bf16 v[16:31], v[144:147], v[6:9], v[16:31]
	ds_read_b64_tr_b16 v[10:11], v244 offset:49216
	ds_read_b64_tr_b16 v[12:13], v244 offset:51776
	v_exp_f32_e32 v6, v151
	v_max3_f32 v144, v148, v135, v87
	v_cvt_pk_bf16_f32 v179, v149, v6
	v_add_f32_e32 v15, v6, v15
	s_waitcnt lgkmcnt(2)
	v_mfma_f32_32x32x16_bf16 v[64:79], v[160:163], v[2:5], v[64:79]
	ds_read_b64_tr_b16 v[6:7], v244 offset:49280
	ds_read_b64_tr_b16 v[8:9], v244 offset:51840
	v_exp_f32_e32 v148, v152
	v_max3_f32 v149, v144, v136, v88
	v_add_f32_e32 v15, v148, v15
	s_waitcnt lgkmcnt(2)
	v_mfma_f32_32x32x16_bf16 v[48:63], v[10:13], v[2:5], v[48:63]
	ds_read_b64_tr_b16 v[144:145], v244 offset:49344
	ds_read_b64_tr_b16 v[146:147], v244 offset:51904
	v_exp_f32_e32 v10, v153
	s_nop 0
	v_cvt_pk_bf16_f32 v180, v148, v10
	v_max3_f32 v148, v149, v137, v89
	v_add_f32_e32 v15, v10, v15
	s_waitcnt lgkmcnt(2)
	v_mfma_f32_32x32x16_bf16 v[32:47], v[6:9], v[2:5], v[32:47]
	ds_read_b64_tr_b16 v[10:11], v244 offset:54272
	ds_read_b64_tr_b16 v[12:13], v244 offset:56832
	v_exp_f32_e32 v149, v154
	v_max3_f32 v148, v148, v138, v90
	v_add_f32_e32 v15, v149, v15
	s_waitcnt lgkmcnt(2)
	v_mfma_f32_32x32x16_bf16 v[16:31], v[144:147], v[2:5], v[16:31]
	ds_read_b64_tr_b16 v[6:7], v244 offset:54336
	ds_read_b64_tr_b16 v[8:9], v244 offset:56896
	v_exp_f32_e32 v2, v155
	v_max3_f32 v144, v148, v139, v91
	v_cvt_pk_bf16_f32 v181, v149, v2
	v_add_f32_e32 v15, v2, v15
	s_waitcnt lgkmcnt(2)
	v_mfma_f32_32x32x16_bf16 v[64:79], v[10:13], v[192:195], v[64:79]
	ds_read_b64_tr_b16 v[2:3], v244 offset:54400
	ds_read_b64_tr_b16 v[4:5], v244 offset:56960
	v_exp_f32_e32 v145, v156
	v_max3_f32 v144, v144, v140, v92
	v_add_f32_e32 v15, v145, v15
	s_waitcnt lgkmcnt(2)
	v_mfma_f32_32x32x16_bf16 v[48:63], v[6:9], v[192:195], v[48:63]
	ds_read_b64_tr_b16 v[10:11], v244 offset:54464
	ds_read_b64_tr_b16 v[12:13], v244 offset:57024
	v_exp_f32_e32 v6, v157
	s_nop 0
	v_add_f32_e32 v7, v6, v15
	v_cvt_pk_bf16_f32 v182, v145, v6
	v_max3_f32 v6, v144, v141, v93
	s_waitcnt lgkmcnt(2)
	v_mfma_f32_32x32x16_bf16 v[32:47], v[2:5], v[192:195], v[32:47]
	v_exp_f32_e32 v3, v158
	v_max3_f32 v4, v6, v142, v94
	v_add_f32_e32 v2, v3, v7
	s_waitcnt lgkmcnt(0)
	v_mfma_f32_32x32x16_bf16 v[16:31], v[10:13], v[192:195], v[16:31]
	v_exp_f32_e32 v5, v159
	s_nop 0
	v_add_f32_e32 v2, v5, v2
	v_cvt_pk_bf16_f32 v183, v3, v5
	v_max3_f32 v3, v4, v143, v95
	v_mov_b32_e32 v4, v2
	s_nop 1
	v_permlane32_swap_b32_e32 v2, v4
	v_cmp_gt_f32_e32 vcc, 1.0, v0
	s_cbranch_vccz .LBB0_570
	v_pk_mul_f32 v[78:79], v[0:1], v[78:79] op_sel_hi:[0,1]
	v_pk_mul_f32 v[76:77], v[0:1], v[76:77] op_sel_hi:[0,1]
	v_pk_mul_f32 v[74:75], v[0:1], v[74:75] op_sel_hi:[0,1]
	v_pk_mul_f32 v[72:73], v[0:1], v[72:73] op_sel_hi:[0,1]
	v_pk_mul_f32 v[70:71], v[0:1], v[70:71] op_sel_hi:[0,1]
	v_pk_mul_f32 v[68:69], v[0:1], v[68:69] op_sel_hi:[0,1]
	v_pk_mul_f32 v[66:67], v[0:1], v[66:67] op_sel_hi:[0,1]
	v_pk_mul_f32 v[64:65], v[0:1], v[64:65] op_sel_hi:[0,1]
	v_pk_mul_f32 v[62:63], v[0:1], v[62:63] op_sel_hi:[0,1]
	v_pk_mul_f32 v[60:61], v[0:1], v[60:61] op_sel_hi:[0,1]
	v_pk_mul_f32 v[58:59], v[0:1], v[58:59] op_sel_hi:[0,1]
	v_pk_mul_f32 v[56:57], v[0:1], v[56:57] op_sel_hi:[0,1]
	v_pk_mul_f32 v[54:55], v[0:1], v[54:55] op_sel_hi:[0,1]
	v_pk_mul_f32 v[52:53], v[0:1], v[52:53] op_sel_hi:[0,1]
	v_pk_mul_f32 v[50:51], v[0:1], v[50:51] op_sel_hi:[0,1]
	v_pk_mul_f32 v[48:49], v[0:1], v[48:49] op_sel_hi:[0,1]
	v_pk_mul_f32 v[46:47], v[0:1], v[46:47] op_sel_hi:[0,1]
	v_pk_mul_f32 v[44:45], v[0:1], v[44:45] op_sel_hi:[0,1]
	v_pk_mul_f32 v[42:43], v[0:1], v[42:43] op_sel_hi:[0,1]
	v_pk_mul_f32 v[40:41], v[0:1], v[40:41] op_sel_hi:[0,1]
	v_pk_mul_f32 v[38:39], v[0:1], v[38:39] op_sel_hi:[0,1]
	v_pk_mul_f32 v[36:37], v[0:1], v[36:37] op_sel_hi:[0,1]
	v_pk_mul_f32 v[34:35], v[0:1], v[34:35] op_sel_hi:[0,1]
	v_pk_mul_f32 v[32:33], v[0:1], v[32:33] op_sel_hi:[0,1]
	v_pk_mul_f32 v[30:31], v[0:1], v[30:31] op_sel_hi:[0,1]
	v_pk_mul_f32 v[28:29], v[0:1], v[28:29] op_sel_hi:[0,1]
	v_pk_mul_f32 v[26:27], v[0:1], v[26:27] op_sel_hi:[0,1]
	v_pk_mul_f32 v[24:25], v[0:1], v[24:25] op_sel_hi:[0,1]
	v_pk_mul_f32 v[22:23], v[0:1], v[22:23] op_sel_hi:[0,1]
	v_pk_mul_f32 v[20:21], v[0:1], v[20:21] op_sel_hi:[0,1]
	v_pk_mul_f32 v[18:19], v[0:1], v[18:19] op_sel_hi:[0,1]
	v_pk_mul_f32 v[16:17], v[0:1], v[16:17] op_sel_hi:[0,1]

.LBB0_582:
	s_add_i32 s13, s12, -1
	s_min_u32 s34, s13, s4
	s_lshl_b64 s[30:31], s[34:35], 13
	v_lshl_add_u64 v[2:3], v[216:217], 0, s[30:31]
	global_load_dwordx4 v[196:199], v[2:3], off
	v_add_co_u32_e32 v2, vcc, s1, v212
	s_nop 1
	v_addc_co_u32_e32 v3, vcc, -1, v213, vcc
	global_load_dwordx4 v[200:203], v[2:3], off offset:-4096
	global_load_dwordx4 v[204:207], v[2:3], off
	ds_read_b128 v[2:5], v243 offset:4608
	ds_read_b128 v[6:9], v243
	ds_read_b128 v[12:15], v242 offset:59392
	s_waitcnt lgkmcnt(0)
	v_mfma_f32_32x32x16_bf16 v[160:175], v[6:9], v[12:15], v[96:111]
	ds_read_b128 v[112:115], v243 offset:32
	ds_read_b128 v[116:119], v242 offset:60416
	v_exp_f32_e32 v0, v128
	v_exp_f32_e32 v6, v129
	v_add_f32_e32 v7, 0, v0
	v_add_f32_e32 v11, v6, v7
	v_cvt_pk_bf16_f32 v10, v0, v6
	v_mfma_f32_32x32x16_bf16 v[144:159], v[2:5], v[12:15], v[96:111]
	ds_read_b128 v[6:9], v243 offset:4640
	v_exp_f32_e32 v0, v130
	v_exp_f32_e32 v120, v131
	v_add_f32_e32 v121, v0, v11
	v_cvt_pk_bf16_f32 v11, v0, v120
	v_add_f32_e32 v0, v120, v121
	s_waitcnt lgkmcnt(1)
	v_mfma_f32_32x32x16_bf16 v[160:175], v[112:115], v[116:119], v[160:175]
	ds_read_b128 v[2:5], v243 offset:64
	ds_read_b128 v[120:123], v242 offset:61440
	v_exp_f32_e32 v12, v132
	v_exp_f32_e32 v13, v133
	v_add_f32_e32 v0, v12, v0
	v_add_f32_e32 v0, v13, v0
	v_cvt_pk_bf16_f32 v12, v12, v13
	s_waitcnt lgkmcnt(2)
	v_mfma_f32_32x32x16_bf16 v[144:159], v[6:9], v[116:119], v[144:159]
	ds_read_b128 v[112:115], v243 offset:4672
	v_exp_f32_e32 v6, v134
	v_exp_f32_e32 v7, v135
	v_add_f32_e32 v0, v6, v0
	v_add_f32_e32 v0, v7, v0
	v_cvt_pk_bf16_f32 v13, v6, v7
	s_waitcnt lgkmcnt(1)
	v_mfma_f32_32x32x16_bf16 v[160:175], v[2:5], v[120:123], v[160:175]
	ds_read_b128 v[116:119], v243 offset:96
	ds_read_b128 v[124:127], v242 offset:62464
	v_exp_f32_e32 v2, v136
	v_exp_f32_e32 v3, v137
	v_add_f32_e32 v0, v2, v0
	v_add_f32_e32 v0, v3, v0
	v_cvt_pk_bf16_f32 v6, v2, v3
	s_waitcnt lgkmcnt(2)
	v_mfma_f32_32x32x16_bf16 v[144:159], v[112:115], v[120:123], v[144:159]
	ds_read_b128 v[2:5], v243 offset:4704
	v_exp_f32_e32 v7, v138
	v_exp_f32_e32 v8, v139
	v_add_f32_e32 v0, v7, v0
	v_add_f32_e32 v0, v8, v0
	v_cvt_pk_bf16_f32 v7, v7, v8
	s_waitcnt lgkmcnt(1)
	v_mfma_f32_32x32x16_bf16 v[160:175], v[116:119], v[124:127], v[160:175]
	ds_read_b64_tr_b16 v[112:113], v244 offset:18432
	ds_read_b64_tr_b16 v[114:115], v244 offset:20992
	v_exp_f32_e32 v8, v140
	v_exp_f32_e32 v9, v141
	v_add_f32_e32 v0, v8, v0
	v_add_f32_e32 v0, v9, v0
	v_cvt_pk_bf16_f32 v8, v8, v9
	s_waitcnt lgkmcnt(2)
	v_mfma_f32_32x32x16_bf16 v[144:159], v[2:5], v[124:127], v[144:159]
	ds_read_b64_tr_b16 v[116:117], v244 offset:18496
	ds_read_b64_tr_b16 v[118:119], v244 offset:21056
	v_exp_f32_e32 v9, v142
	v_exp_f32_e32 v14, v143
	v_add_f32_e32 v0, v9, v0
	v_add_f32_e32 v0, v14, v0
	v_cvt_pk_bf16_f32 v9, v9, v14
	s_waitcnt lgkmcnt(2)
	v_mfma_f32_32x32x16_bf16 v[64:79], v[112:115], v[188:191], v[64:79]
	ds_read_b64_tr_b16 v[120:121], v244 offset:18560
	ds_read_b64_tr_b16 v[122:123], v244 offset:21120
	v_exp_f32_e32 v2, v80
	v_max3_f32 v3, v160, s33, v144
	v_add_f32_e32 v0, v2, v0
	s_waitcnt lgkmcnt(2)
	v_mfma_f32_32x32x16_bf16 v[48:63], v[116:119], v[188:191], v[48:63]
	ds_read_b64_tr_b16 v[112:113], v244 offset:18624
	ds_read_b64_tr_b16 v[114:115], v244 offset:21184
	v_exp_f32_e32 v4, v81
	v_max3_f32 v3, v3, v161, v145
	v_add_f32_e32 v0, v4, v0
	v_cvt_pk_bf16_f32 v2, v2, v4
	s_waitcnt lgkmcnt(2)
	v_mfma_f32_32x32x16_bf16 v[32:47], v[120:123], v[188:191], v[32:47]
	ds_read_b64_tr_b16 v[116:117], v244 offset:23552
	ds_read_b64_tr_b16 v[118:119], v244 offset:26112
	v_exp_f32_e32 v4, v82
	v_max3_f32 v5, v3, v162, v146
	v_add_f32_e32 v0, v4, v0
	s_waitcnt lgkmcnt(2)
	v_mfma_f32_32x32x16_bf16 v[16:31], v[112:115], v[188:191], v[16:31]
	ds_read_b64_tr_b16 v[120:121], v244 offset:23616
	ds_read_b64_tr_b16 v[122:123], v244 offset:26176
	v_exp_f32_e32 v3, v83
	s_nop 0
	v_add_f32_e32 v0, v3, v0
	v_cvt_pk_bf16_f32 v3, v4, v3
	v_max3_f32 v4, v5, v163, v147
	s_waitcnt lgkmcnt(2)
	v_mfma_f32_32x32x16_bf16 v[64:79], v[116:119], v[184:187], v[64:79]
	ds_read_b64_tr_b16 v[80:81], v244 offset:23680
	ds_read_b64_tr_b16 v[82:83], v244 offset:26240
	v_exp_f32_e32 v5, v84
	v_max3_f32 v14, v4, v164, v148
	v_add_f32_e32 v0, v5, v0
	s_waitcnt lgkmcnt(2)
	v_mfma_f32_32x32x16_bf16 v[48:63], v[120:123], v[184:187], v[48:63]
	ds_read_b64_tr_b16 v[112:113], v244 offset:23744
	ds_read_b64_tr_b16 v[114:115], v244 offset:26304
	v_exp_f32_e32 v4, v85
	s_nop 0
	v_add_f32_e32 v0, v4, v0
	v_cvt_pk_bf16_f32 v4, v5, v4
	v_max3_f32 v5, v14, v165, v149
	s_waitcnt lgkmcnt(2)
	v_mfma_f32_32x32x16_bf16 v[32:47], v[80:83], v[184:187], v[32:47]
	ds_read_b64_tr_b16 v[116:117], v244 offset:28672
	ds_read_b64_tr_b16 v[118:119], v244 offset:31232
	v_exp_f32_e32 v14, v86
	v_max3_f32 v15, v5, v166, v150
	v_add_f32_e32 v0, v14, v0
	s_waitcnt lgkmcnt(2)
	v_mfma_f32_32x32x16_bf16 v[16:31], v[112:115], v[184:187], v[16:31]
	ds_read_b64_tr_b16 v[80:81], v244 offset:28736
	ds_read_b64_tr_b16 v[82:83], v244 offset:31296
	v_exp_f32_e32 v5, v87
	s_nop 0
	v_add_f32_e32 v0, v5, v0
	v_cvt_pk_bf16_f32 v5, v14, v5
	v_max3_f32 v14, v15, v167, v151
	s_waitcnt lgkmcnt(2)
	v_mfma_f32_32x32x16_bf16 v[64:79], v[116:119], v[176:179], v[64:79]
	ds_read_b64_tr_b16 v[84:85], v244 offset:28800
	ds_read_b64_tr_b16 v[86:87], v244 offset:31360
	v_exp_f32_e32 v15, v88
	v_max3_f32 v14, v14, v168, v152
	v_add_f32_e32 v0, v15, v0
	s_waitcnt lgkmcnt(2)
	v_mfma_f32_32x32x16_bf16 v[48:63], v[80:83], v[176:179], v[48:63]
	ds_read_b64_tr_b16 v[112:113], v244 offset:28864
	ds_read_b64_tr_b16 v[114:115], v244 offset:31424
	v_exp_f32_e32 v80, v89
	v_max3_f32 v14, v14, v169, v153
	v_add_f32_e32 v0, v80, v0
	v_cvt_pk_bf16_f32 v192, v15, v80
	s_waitcnt lgkmcnt(2)
	v_mfma_f32_32x32x16_bf16 v[32:47], v[84:87], v[176:179], v[32:47]
	ds_read_b64_tr_b16 v[80:81], v244 offset:33792
	ds_read_b64_tr_b16 v[82:83], v244 offset:36352
	v_exp_f32_e32 v15, v90
	v_max3_f32 v14, v14, v170, v154
	v_add_f32_e32 v0, v15, v0
	s_waitcnt lgkmcnt(2)
	v_mfma_f32_32x32x16_bf16 v[16:31], v[112:115], v[176:179], v[16:31]
	ds_read_b64_tr_b16 v[84:85], v244 offset:33856
	ds_read_b64_tr_b16 v[86:87], v244 offset:36416
	v_exp_f32_e32 v88, v91
	v_max3_f32 v14, v14, v171, v155
	v_add_f32_e32 v0, v88, v0
	v_cvt_pk_bf16_f32 v193, v15, v88
	s_waitcnt lgkmcnt(2)
	v_mfma_f32_32x32x16_bf16 v[64:79], v[80:83], v[180:183], v[64:79]
	ds_read_b64_tr_b16 v[88:89], v244 offset:33920
	ds_read_b64_tr_b16 v[90:91], v244 offset:36480
	v_exp_f32_e32 v15, v92
	v_max3_f32 v14, v14, v172, v156
	v_add_f32_e32 v0, v15, v0
	s_waitcnt lgkmcnt(2)
	v_mfma_f32_32x32x16_bf16 v[48:63], v[84:87], v[180:183], v[48:63]
	ds_read_b64_tr_b16 v[80:81], v244 offset:33984
	ds_read_b64_tr_b16 v[82:83], v244 offset:36544
	v_exp_f32_e32 v84, v93
	v_max3_f32 v14, v14, v173, v157
	v_add_f32_e32 v0, v84, v0
	v_cvt_pk_bf16_f32 v194, v15, v84
	s_waitcnt lgkmcnt(2)
	v_mfma_f32_32x32x16_bf16 v[32:47], v[88:91], v[180:183], v[32:47]
	v_exp_f32_e32 v15, v94
	v_max3_f32 v14, v14, v174, v158
	v_add_f32_e32 v0, v15, v0
	s_waitcnt lgkmcnt(0)
	v_mfma_f32_32x32x16_bf16 v[16:31], v[80:83], v[180:183], v[16:31]
	v_exp_f32_e32 v80, v95
	s_nop 0
	v_add_f32_e32 v0, v80, v0
	v_cvt_pk_bf16_f32 v195, v15, v80
	v_max3_f32 v15, v14, v175, v159
	v_mov_b32_e32 v14, v0
	s_nop 1
	v_permlane32_swap_b32_e32 v0, v14
	v_cmp_gt_f32_e32 vcc, 1.0, v220
	s_cbranch_vccz .LBB0_584
	v_pk_mul_f32 v[78:79], v[220:221], v[78:79] op_sel_hi:[0,1]
	v_pk_mul_f32 v[76:77], v[220:221], v[76:77] op_sel_hi:[0,1]
	v_pk_mul_f32 v[74:75], v[220:221], v[74:75] op_sel_hi:[0,1]
	v_pk_mul_f32 v[72:73], v[220:221], v[72:73] op_sel_hi:[0,1]
	v_pk_mul_f32 v[70:71], v[220:221], v[70:71] op_sel_hi:[0,1]
	v_pk_mul_f32 v[68:69], v[220:221], v[68:69] op_sel_hi:[0,1]
	v_pk_mul_f32 v[66:67], v[220:221], v[66:67] op_sel_hi:[0,1]
	v_pk_mul_f32 v[64:65], v[220:221], v[64:65] op_sel_hi:[0,1]
	v_pk_mul_f32 v[62:63], v[220:221], v[62:63] op_sel_hi:[0,1]
	v_pk_mul_f32 v[60:61], v[220:221], v[60:61] op_sel_hi:[0,1]
	v_pk_mul_f32 v[58:59], v[220:221], v[58:59] op_sel_hi:[0,1]
	v_pk_mul_f32 v[56:57], v[220:221], v[56:57] op_sel_hi:[0,1]
	v_pk_mul_f32 v[54:55], v[220:221], v[54:55] op_sel_hi:[0,1]
	v_pk_mul_f32 v[52:53], v[220:221], v[52:53] op_sel_hi:[0,1]
	v_pk_mul_f32 v[50:51], v[220:221], v[50:51] op_sel_hi:[0,1]
	v_pk_mul_f32 v[48:49], v[220:221], v[48:49] op_sel_hi:[0,1]
	v_pk_mul_f32 v[46:47], v[220:221], v[46:47] op_sel_hi:[0,1]
	v_pk_mul_f32 v[44:45], v[220:221], v[44:45] op_sel_hi:[0,1]
	v_pk_mul_f32 v[42:43], v[220:221], v[42:43] op_sel_hi:[0,1]
	v_pk_mul_f32 v[40:41], v[220:221], v[40:41] op_sel_hi:[0,1]
	v_pk_mul_f32 v[38:39], v[220:221], v[38:39] op_sel_hi:[0,1]
	v_pk_mul_f32 v[36:37], v[220:221], v[36:37] op_sel_hi:[0,1]
	v_pk_mul_f32 v[34:35], v[220:221], v[34:35] op_sel_hi:[0,1]
	v_pk_mul_f32 v[32:33], v[220:221], v[32:33] op_sel_hi:[0,1]
	v_pk_mul_f32 v[30:31], v[220:221], v[30:31] op_sel_hi:[0,1]
	v_pk_mul_f32 v[28:29], v[220:221], v[28:29] op_sel_hi:[0,1]
	v_pk_mul_f32 v[26:27], v[220:221], v[26:27] op_sel_hi:[0,1]
	v_pk_mul_f32 v[24:25], v[220:221], v[24:25] op_sel_hi:[0,1]
	v_pk_mul_f32 v[22:23], v[220:221], v[22:23] op_sel_hi:[0,1]
	v_pk_mul_f32 v[20:21], v[220:221], v[20:21] op_sel_hi:[0,1]
	v_pk_mul_f32 v[18:19], v[220:221], v[18:19] op_sel_hi:[0,1]
	v_pk_mul_f32 v[16:17], v[220:221], v[16:17] op_sel_hi:[0,1]

.LBB0_587:
	s_min_u32 s34, s12, s4
	s_waitcnt vmcnt(2)
	ds_write_b128 v241, v[196:199] offset:9216
	s_waitcnt vmcnt(1)
	ds_write_b128 v240, v[200:203] offset:38912
	s_waitcnt vmcnt(0)
	ds_write_b128 v240, v[204:207] offset:49152
	s_lshl_b64 s[30:31], s[34:35], 13
	s_waitcnt lgkmcnt(0)
	s_barrier
	v_lshl_add_u64 v[80:81], v[216:217], 0, s[30:31]
	global_load_dwordx4 v[196:199], v[80:81], off
	global_load_dwordx4 v[200:203], v[212:213], off offset:-4096
	global_load_dwordx4 v[204:207], v[212:213], off
	ds_read_b128 v[176:179], v243 offset:13824
	ds_read_b128 v[80:83], v243 offset:9216
	ds_read_b128 v[180:183], v242 offset:59392
	s_waitcnt lgkmcnt(0)
	v_mfma_f32_32x32x16_bf16 v[128:143], v[80:83], v[180:183], v[112:127]
	ds_read_b128 v[184:187], v243 offset:9248
	ds_read_b128 v[222:225], v242 offset:60416
	v_exp_f32_e32 v15, v160
	v_exp_f32_e32 v80, v161
	v_add_f32_e32 v81, 0, v15
	v_add_f32_e32 v81, v80, v81
	v_cvt_pk_bf16_f32 v188, v15, v80
	v_exp_f32_e32 v15, v162
	v_exp_f32_e32 v80, v163
	ds_read_b128 v[160:163], v243 offset:13856
	v_add_f32_e32 v81, v15, v81
	v_cvt_pk_bf16_f32 v189, v15, v80
	v_add_f32_e32 v15, v80, v81
	v_mfma_f32_32x32x16_bf16 v[80:95], v[176:179], v[180:183], v[112:127]
	s_waitcnt lgkmcnt(1)
	v_mfma_f32_32x32x16_bf16 v[128:143], v[184:187], v[222:225], v[128:143]
	ds_read_b128 v[176:179], v243 offset:9280
	ds_read_b128 v[180:183], v242 offset:61440
	v_exp_f32_e32 v164, v164
	v_exp_f32_e32 v165, v165
	v_add_f32_e32 v15, v164, v15
	v_cvt_pk_bf16_f32 v190, v164, v165
	v_add_f32_e32 v15, v165, v15
	s_waitcnt lgkmcnt(2)
	v_mfma_f32_32x32x16_bf16 v[80:95], v[160:163], v[222:225], v[80:95]
	ds_read_b128 v[234:237], v243 offset:13888
	v_exp_f32_e32 v160, v166
	v_exp_f32_e32 v161, v167
	v_add_f32_e32 v15, v160, v15
	v_cvt_pk_bf16_f32 v191, v160, v161
	v_add_f32_e32 v15, v161, v15
	s_waitcnt lgkmcnt(1)
	v_mfma_f32_32x32x16_bf16 v[128:143], v[176:179], v[180:183], v[128:143]
	ds_read_b128 v[160:163], v243 offset:9312
	ds_read_b128 v[164:167], v242 offset:62464
	v_exp_f32_e32 v168, v168
	v_exp_f32_e32 v169, v169
	v_add_f32_e32 v15, v168, v15
	v_cvt_pk_bf16_f32 v184, v168, v169
	v_add_f32_e32 v15, v169, v15
	s_waitcnt lgkmcnt(2)
	v_mfma_f32_32x32x16_bf16 v[80:95], v[234:237], v[180:183], v[80:95]
	ds_read_b128 v[176:179], v243 offset:13920
	v_exp_f32_e32 v168, v170
	v_exp_f32_e32 v169, v171
	v_add_f32_e32 v15, v168, v15
	v_cvt_pk_bf16_f32 v185, v168, v169
	v_add_f32_e32 v15, v169, v15
	s_waitcnt lgkmcnt(1)
	v_mfma_f32_32x32x16_bf16 v[128:143], v[160:163], v[164:167], v[128:143]
	ds_read_b64_tr_b16 v[168:169], v244 offset:38912
	ds_read_b64_tr_b16 v[170:171], v244 offset:41472
	v_exp_f32_e32 v160, v172
	v_exp_f32_e32 v161, v173
	v_add_f32_e32 v15, v160, v15
	v_cvt_pk_bf16_f32 v186, v160, v161
	v_add_f32_e32 v15, v161, v15
	s_waitcnt lgkmcnt(2)
	v_mfma_f32_32x32x16_bf16 v[80:95], v[176:179], v[164:167], v[80:95]
	ds_read_b64_tr_b16 v[160:161], v244 offset:38976
	ds_read_b64_tr_b16 v[162:163], v244 offset:41536
	v_exp_f32_e32 v172, v174
	v_exp_f32_e32 v173, v175
	v_add_f32_e32 v15, v172, v15
	v_cvt_pk_bf16_f32 v187, v172, v173
	v_add_f32_e32 v15, v173, v15
	s_waitcnt lgkmcnt(2)
	v_mfma_f32_32x32x16_bf16 v[64:79], v[168:171], v[10:13], v[64:79]
	ds_read_b64_tr_b16 v[164:165], v244 offset:39040
	ds_read_b64_tr_b16 v[166:167], v244 offset:41600
	v_exp_f32_e32 v144, v144
	v_max3_f32 v172, v128, s33, v80
	v_add_f32_e32 v15, v144, v15
	s_waitcnt lgkmcnt(2)
	v_mfma_f32_32x32x16_bf16 v[48:63], v[160:163], v[10:13], v[48:63]
	ds_read_b64_tr_b16 v[168:169], v244 offset:39104
	ds_read_b64_tr_b16 v[170:171], v244 offset:41664
	v_exp_f32_e32 v145, v145
	s_nop 0
	v_cvt_pk_bf16_f32 v176, v144, v145
	v_max3_f32 v144, v172, v129, v81
	v_add_f32_e32 v15, v145, v15
	s_waitcnt lgkmcnt(2)
	v_mfma_f32_32x32x16_bf16 v[32:47], v[164:167], v[10:13], v[32:47]
	ds_read_b64_tr_b16 v[160:161], v244 offset:44032
	ds_read_b64_tr_b16 v[162:163], v244 offset:46592
	v_exp_f32_e32 v145, v146
	v_max3_f32 v144, v144, v130, v82
	v_add_f32_e32 v15, v145, v15
	s_waitcnt lgkmcnt(2)
	v_mfma_f32_32x32x16_bf16 v[16:31], v[168:171], v[10:13], v[16:31]
	ds_read_b64_tr_b16 v[164:165], v244 offset:44096
	ds_read_b64_tr_b16 v[166:167], v244 offset:46656
	v_exp_f32_e32 v10, v147
	v_max3_f32 v144, v144, v131, v83
	v_cvt_pk_bf16_f32 v177, v145, v10
	v_add_f32_e32 v15, v10, v15
	s_waitcnt lgkmcnt(2)
	v_mfma_f32_32x32x16_bf16 v[64:79], v[160:163], v[6:9], v[64:79]
	ds_read_b64_tr_b16 v[10:11], v244 offset:44160
	ds_read_b64_tr_b16 v[12:13], v244 offset:46720
	v_exp_f32_e32 v148, v148
	v_max3_f32 v160, v144, v132, v84
	v_add_f32_e32 v15, v148, v15
	s_waitcnt lgkmcnt(2)
	v_mfma_f32_32x32x16_bf16 v[48:63], v[164:167], v[6:9], v[48:63]
	ds_read_b64_tr_b16 v[144:145], v244 offset:44224
	ds_read_b64_tr_b16 v[146:147], v244 offset:46784
	v_exp_f32_e32 v149, v149
	s_nop 0
	v_cvt_pk_bf16_f32 v178, v148, v149
	v_max3_f32 v148, v160, v133, v85
	v_add_f32_e32 v15, v149, v15
	s_waitcnt lgkmcnt(2)
	v_mfma_f32_32x32x16_bf16 v[32:47], v[10:13], v[6:9], v[32:47]
	ds_read_b64_tr_b16 v[160:161], v244 offset:49152
	ds_read_b64_tr_b16 v[162:163], v244 offset:51712
	v_exp_f32_e32 v149, v150
	v_max3_f32 v148, v148, v134, v86
	v_add_f32_e32 v15, v149, v15
	s_waitcnt lgkmcnt(2)
	v_mfma_f32_32x32x16_bf16 v[16:31], v[144:147], v[6:9], v[16:31]
	ds_read_b64_tr_b16 v[10:11], v244 offset:49216
	ds_read_b64_tr_b16 v[12:13], v244 offset:51776
	v_exp_f32_e32 v6, v151
	v_max3_f32 v144, v148, v135, v87
	v_cvt_pk_bf16_f32 v179, v149, v6
	v_add_f32_e32 v15, v6, v15
	s_waitcnt lgkmcnt(2)
	v_mfma_f32_32x32x16_bf16 v[64:79], v[160:163], v[2:5], v[64:79]
	ds_read_b64_tr_b16 v[6:7], v244 offset:49280
	ds_read_b64_tr_b16 v[8:9], v244 offset:51840
	v_exp_f32_e32 v148, v152
	v_max3_f32 v149, v144, v136, v88
	v_add_f32_e32 v15, v148, v15
	s_waitcnt lgkmcnt(2)
	v_mfma_f32_32x32x16_bf16 v[48:63], v[10:13], v[2:5], v[48:63]
	ds_read_b64_tr_b16 v[144:145], v244 offset:49344
	ds_read_b64_tr_b16 v[146:147], v244 offset:51904
	v_exp_f32_e32 v10, v153
	s_nop 0
	v_cvt_pk_bf16_f32 v180, v148, v10
	v_max3_f32 v148, v149, v137, v89
	v_add_f32_e32 v15, v10, v15
	s_waitcnt lgkmcnt(2)
	v_mfma_f32_32x32x16_bf16 v[32:47], v[6:9], v[2:5], v[32:47]
	ds_read_b64_tr_b16 v[10:11], v244 offset:54272
	ds_read_b64_tr_b16 v[12:13], v244 offset:56832
	v_exp_f32_e32 v149, v154
	v_max3_f32 v148, v148, v138, v90
	v_add_f32_e32 v15, v149, v15
	s_waitcnt lgkmcnt(2)
	v_mfma_f32_32x32x16_bf16 v[16:31], v[144:147], v[2:5], v[16:31]
	ds_read_b64_tr_b16 v[6:7], v244 offset:54336
	ds_read_b64_tr_b16 v[8:9], v244 offset:56896
	v_exp_f32_e32 v2, v155
	v_max3_f32 v144, v148, v139, v91
	v_cvt_pk_bf16_f32 v181, v149, v2
	v_add_f32_e32 v15, v2, v15
	s_waitcnt lgkmcnt(2)
	v_mfma_f32_32x32x16_bf16 v[64:79], v[10:13], v[192:195], v[64:79]
	ds_read_b64_tr_b16 v[2:3], v244 offset:54400
	ds_read_b64_tr_b16 v[4:5], v244 offset:56960
	v_exp_f32_e32 v145, v156
	v_max3_f32 v144, v144, v140, v92
	v_add_f32_e32 v15, v145, v15
	s_waitcnt lgkmcnt(2)
	v_mfma_f32_32x32x16_bf16 v[48:63], v[6:9], v[192:195], v[48:63]
	ds_read_b64_tr_b16 v[10:11], v244 offset:54464
	ds_read_b64_tr_b16 v[12:13], v244 offset:57024
	v_exp_f32_e32 v6, v157
	s_nop 0
	v_add_f32_e32 v7, v6, v15
	v_cvt_pk_bf16_f32 v182, v145, v6
	v_max3_f32 v6, v144, v141, v93
	s_waitcnt lgkmcnt(2)
	v_mfma_f32_32x32x16_bf16 v[32:47], v[2:5], v[192:195], v[32:47]
	v_exp_f32_e32 v3, v158
	v_max3_f32 v4, v6, v142, v94
	v_add_f32_e32 v2, v3, v7
	s_waitcnt lgkmcnt(0)
	v_mfma_f32_32x32x16_bf16 v[16:31], v[10:13], v[192:195], v[16:31]
	v_exp_f32_e32 v5, v159
	s_nop 0
	v_add_f32_e32 v2, v5, v2
	v_cvt_pk_bf16_f32 v183, v3, v5
	v_max3_f32 v3, v4, v143, v95
	v_mov_b32_e32 v4, v2
	s_nop 1
	v_permlane32_swap_b32_e32 v2, v4
	v_cmp_gt_f32_e32 vcc, 1.0, v0
	s_cbranch_vccz .LBB0_589
	v_pk_mul_f32 v[78:79], v[0:1], v[78:79] op_sel_hi:[0,1]
	v_pk_mul_f32 v[76:77], v[0:1], v[76:77] op_sel_hi:[0,1]
	v_pk_mul_f32 v[74:75], v[0:1], v[74:75] op_sel_hi:[0,1]
	v_pk_mul_f32 v[72:73], v[0:1], v[72:73] op_sel_hi:[0,1]
	v_pk_mul_f32 v[70:71], v[0:1], v[70:71] op_sel_hi:[0,1]
	v_pk_mul_f32 v[68:69], v[0:1], v[68:69] op_sel_hi:[0,1]
	v_pk_mul_f32 v[66:67], v[0:1], v[66:67] op_sel_hi:[0,1]
	v_pk_mul_f32 v[64:65], v[0:1], v[64:65] op_sel_hi:[0,1]
	v_pk_mul_f32 v[62:63], v[0:1], v[62:63] op_sel_hi:[0,1]
	v_pk_mul_f32 v[60:61], v[0:1], v[60:61] op_sel_hi:[0,1]
	v_pk_mul_f32 v[58:59], v[0:1], v[58:59] op_sel_hi:[0,1]
	v_pk_mul_f32 v[56:57], v[0:1], v[56:57] op_sel_hi:[0,1]
	v_pk_mul_f32 v[54:55], v[0:1], v[54:55] op_sel_hi:[0,1]
	v_pk_mul_f32 v[52:53], v[0:1], v[52:53] op_sel_hi:[0,1]
	v_pk_mul_f32 v[50:51], v[0:1], v[50:51] op_sel_hi:[0,1]
	v_pk_mul_f32 v[48:49], v[0:1], v[48:49] op_sel_hi:[0,1]
	v_pk_mul_f32 v[46:47], v[0:1], v[46:47] op_sel_hi:[0,1]
	v_pk_mul_f32 v[44:45], v[0:1], v[44:45] op_sel_hi:[0,1]
	v_pk_mul_f32 v[42:43], v[0:1], v[42:43] op_sel_hi:[0,1]
	v_pk_mul_f32 v[40:41], v[0:1], v[40:41] op_sel_hi:[0,1]
	v_pk_mul_f32 v[38:39], v[0:1], v[38:39] op_sel_hi:[0,1]
	v_pk_mul_f32 v[36:37], v[0:1], v[36:37] op_sel_hi:[0,1]
	v_pk_mul_f32 v[34:35], v[0:1], v[34:35] op_sel_hi:[0,1]
	v_pk_mul_f32 v[32:33], v[0:1], v[32:33] op_sel_hi:[0,1]
	v_pk_mul_f32 v[30:31], v[0:1], v[30:31] op_sel_hi:[0,1]
	v_pk_mul_f32 v[28:29], v[0:1], v[28:29] op_sel_hi:[0,1]
	v_pk_mul_f32 v[26:27], v[0:1], v[26:27] op_sel_hi:[0,1]
	v_pk_mul_f32 v[24:25], v[0:1], v[24:25] op_sel_hi:[0,1]
	v_pk_mul_f32 v[22:23], v[0:1], v[22:23] op_sel_hi:[0,1]
	v_pk_mul_f32 v[20:21], v[0:1], v[20:21] op_sel_hi:[0,1]
	v_pk_mul_f32 v[18:19], v[0:1], v[18:19] op_sel_hi:[0,1]
	v_pk_mul_f32 v[16:17], v[0:1], v[16:17] op_sel_hi:[0,1]
